# final RMSNorm row loop: gamma hoisted, 4 chunk loads per row issued together, next-row loads ahead of stores
# speedup vs baseline: 1.0046x; 1.0022x over previous
.LBB0_1386:
	global_load_dwordx4 v[20:23], v[0:1], off
	global_load_dwordx4 v[24:27], v[0:1], off offset:1024
	global_load_dwordx4 v[28:31], v[0:1], off offset:2048
	global_load_dwordx4 v[32:35], v[0:1], off offset:3072
	v_mov_b32_e32 v54, 0
	s_and_saveexec_b64 s[0:1], vcc
	global_load_dword v54, v[2:3], off
	s_or_b64 exec, exec, s[0:1]
	global_load_dwordx2 v[14:15], v[4:5], off offset:-1024
	global_load_dwordx2 v[36:37], v[4:5], off offset:-512
	global_load_dwordx2 v[38:39], v[4:5], off
	global_load_dwordx2 v[40:41], v[4:5], off offset:512
	v_lshl_add_u64 v[2:3], v[2:3], 0, s[2:3]
	v_lshl_add_u64 v[4:5], v[4:5], 0, s[4:5]
	s_waitcnt vmcnt(0)
.Lfn_loop:
	s_waitcnt vmcnt(4)
	ds_swizzle_b32 v16, v54 offset:swizzle(SWAP,1)
	s_add_i32 s8, s8, s12
	s_waitcnt lgkmcnt(0)
	v_add_f32_e32 v9, v54, v16
	ds_swizzle_b32 v16, v9 offset:swizzle(SWAP,2)
	s_waitcnt lgkmcnt(0)
	v_add_f32_e32 v9, v9, v16
	ds_swizzle_b32 v16, v9 offset:swizzle(SWAP,4)
	s_waitcnt lgkmcnt(0)
	v_add_f32_e32 v9, v9, v16
	ds_swizzle_b32 v16, v9 offset:swizzle(SWAP,8)
	s_waitcnt lgkmcnt(0)
	v_add_f32_e32 v9, v9, v16
	ds_swizzle_b32 v16, v9 offset:swizzle(SWAP,16)
	s_waitcnt lgkmcnt(0)
	v_add_f32_e32 v9, v9, v16
	v_mov_b32_e32 v16, v9
	s_nop 1
	v_permlane32_swap_b32_e32 v9, v16
	v_add_f32_e32 v9, v9, v16
	v_fmamk_f32 v9, v9, 0x3a800000, v8
	v_mul_f32_e32 v16, 0x4b800000, v9
	v_cmp_gt_f32_e64 s[0:1], s9, v9
	v_lshlrev_b32_e32 v18, 16, v14
	v_cndmask_b32_e64 v9, v9, v16, s[0:1]
	v_rsq_f32_e32 v9, v9
	v_and_b32_e32 v19, 0xffff0000, v14
	v_lshlrev_b32_e32 v14, 16, v15
	v_and_b32_e32 v15, 0xffff0000, v15
	v_mul_f32_e32 v16, 0x45800000, v9
	v_cndmask_b32_e64 v16, v9, v16, s[0:1]
	v_pk_mul_f32 v[18:19], v[16:17], v[18:19] op_sel_hi:[0,1]
	v_pk_mul_f32 v[14:15], v[16:17], v[14:15] op_sel_hi:[0,1]
	v_pk_mul_f32 v[12:13], v[22:23], v[14:15]
	v_pk_mul_f32 v[10:11], v[20:21], v[18:19]
	v_lshlrev_b32_e32 v18, 16, v36
	v_and_b32_e32 v19, 0xffff0000, v36
	v_lshlrev_b32_e32 v36, 16, v37
	v_and_b32_e32 v37, 0xffff0000, v37
	v_pk_mul_f32 v[18:19], v[16:17], v[18:19] op_sel_hi:[0,1]
	v_pk_mul_f32 v[36:37], v[16:17], v[36:37] op_sel_hi:[0,1]
	v_pk_mul_f32 v[44:45], v[26:27], v[36:37]
	v_pk_mul_f32 v[42:43], v[24:25], v[18:19]
	v_lshlrev_b32_e32 v18, 16, v38
	v_and_b32_e32 v19, 0xffff0000, v38
	v_lshlrev_b32_e32 v38, 16, v39
	v_and_b32_e32 v39, 0xffff0000, v39
	v_pk_mul_f32 v[18:19], v[16:17], v[18:19] op_sel_hi:[0,1]
	v_pk_mul_f32 v[38:39], v[16:17], v[38:39] op_sel_hi:[0,1]
	v_pk_mul_f32 v[48:49], v[30:31], v[38:39]
	v_pk_mul_f32 v[46:47], v[28:29], v[18:19]
	v_lshlrev_b32_e32 v18, 16, v40
	v_and_b32_e32 v19, 0xffff0000, v40
	v_lshlrev_b32_e32 v40, 16, v41
	v_and_b32_e32 v41, 0xffff0000, v41
	v_pk_mul_f32 v[18:19], v[16:17], v[18:19] op_sel_hi:[0,1]
	v_pk_mul_f32 v[40:41], v[16:17], v[40:41] op_sel_hi:[0,1]
	v_pk_mul_f32 v[52:53], v[34:35], v[40:41]
	v_pk_mul_f32 v[50:51], v[32:33], v[18:19]
	s_cmpk_gt_i32 s8, 0x3fff
	s_cbranch_scc1 .Lfn_skip
	s_and_saveexec_b64 s[0:1], vcc
	global_load_dword v54, v[2:3], off
	s_or_b64 exec, exec, s[0:1]
	global_load_dwordx2 v[14:15], v[4:5], off offset:-1024
	global_load_dwordx2 v[36:37], v[4:5], off offset:-512
	global_load_dwordx2 v[38:39], v[4:5], off
	global_load_dwordx2 v[40:41], v[4:5], off offset:512
	v_lshl_add_u64 v[2:3], v[2:3], 0, s[2:3]
	v_lshl_add_u64 v[4:5], v[4:5], 0, s[4:5]
.Lfn_skip:
	global_store_dwordx4 v[6:7], v[10:13], off offset:-2048
	global_store_dwordx4 v[6:7], v[42:45], off offset:-1024
	global_store_dwordx4 v[6:7], v[46:49], off
	global_store_dwordx4 v[6:7], v[50:53], off offset:1024
	v_lshl_add_u64 v[6:7], v[6:7], 0, s[6:7]
	s_cmpk_gt_i32 s8, 0x3fff
	s_cbranch_scc0 .Lfn_loop
